# prompt attention: V^T tile stored key-permuted in LDS so each PV A-fragment is one ds_read_b128 (was a ds_read2_b64 pair)
# speedup vs baseline: 1.0266x; 1.0076x over previous
; template <int DK, int DV, int KT, bool SAMPLE>
; DI void attn_item(CP c, int l, int qb, int h, unsigned char* sm) {
;     ...
;     const int ntiles = SAMPLE ? 66 : 2 * qb + 2; const int nj = ntiles / 2;
;     const bool wave_on = SAMPLE ? (wq < 2) : true;
;     const int qc = 2 * qb + (wq >> 1);
;     f32x16 Oacc[NDT];
; #pragma unroll
;     for (int d = 0; d < NDT; ++d)
; #pragma unroll
;         for (int i = 0; i < 16; ++i) Oacc[d][i] = 0.f;
;     float m_run = -INFINITY, l_run = 0.f;
;     const float scale = 0.07216878364870322f * 1.4426950408889634f;
;     u32x4 kreg[6], vreg[4];
;     const int lkey = gt >> 2, ls0 = gt & 3, ldv = gt >> 1, lv0 = gt & 1;
;     const bf16_t* kn_base = KNg + (size_t)lkey * 512 + h * 128 + ls0 * 8; const bf16_t* kp_base = KPEg + (size_t)lkey * 64 + ls0 * 8;
;     const bf16_t* vt_base = VTg + (size_t)(h * 128 + ldv) * MP + lv0 * 8;
;     ...
;     if (!SAMPLE) ATT_ISSUE(g);
.LBB0_645:
	s_or_b64 exec, exec, s[12:13]
	v_bfe_u32 v8, v167, 2, 6
	v_lshlrev_b32_e32 v0, 10, v8
	v_ashrrev_i32_e32 v154, 8, v167
	v_lshl_add_u64 v[2:3], s[54:55], 0, v[0:1]
	v_lshlrev_b32_e32 v152, 7, v5
	v_lshlrev_b32_e32 v0, 8, v5
	v_lshlrev_b32_e32 v5, 4, v167
	v_lshl_add_u64 v[2:3], v[2:3], 0, v[0:1]
	v_and_b32_e32 v0, 48, v5
	v_ashrrev_i32_e32 v155, 31, v154
	v_lshl_add_u64 v[156:157], v[2:3], 0, v[0:1]
	v_lshlrev_b32_e32 v2, 7, v8
	v_mov_b32_e32 v3, v1
	v_lshlrev_b64 v[6:7], 16, v[154:155]
	v_bfe_u32 v9, v167, 1, 7
	v_lshl_add_u64 v[2:3], s[56:57], 0, v[2:3]
	v_lshl_add_u64 v[6:7], v[156:157], 0, v[6:7]
	v_or_b32_e32 v10, v9, v152
	global_load_dwordx4 v[112:115], v[6:7], off
	global_load_dwordx4 v[116:119], v[6:7], off offset:64
	global_load_dwordx4 v[120:123], v[6:7], off offset:128
	global_load_dwordx4 v[124:127], v[6:7], off offset:192
	v_lshl_add_u64 v[158:159], v[2:3], 0, v[0:1]
	v_lshlrev_b64 v[6:7], 13, v[154:155]
	v_lshlrev_b32_e32 v2, 15, v10
	v_mov_b32_e32 v3, v1
	v_lshl_add_u64 v[6:7], v[158:159], 0, v[6:7]
	v_lshl_add_u64 v[2:3], s[58:59], 0, v[2:3]
	global_load_dwordx4 v[128:131], v[6:7], off
	global_load_dwordx4 v[132:135], v[6:7], off offset:64
	v_and_b32_e32 v6, 16, v5
	v_mov_b32_e32 v7, v1
	v_lshl_add_u64 v[164:165], v[2:3], 0, v[6:7]
	v_lshlrev_b64 v[2:3], 7, v[154:155]
	v_lshl_add_u64 v[2:3], v[164:165], 0, v[2:3]
	global_load_dwordx4 v[136:139], v[2:3], off
	global_load_dwordx4 v[140:143], v[2:3], off offset:32
	global_load_dwordx4 v[144:147], v[2:3], off offset:64
	global_load_dwordx4 v[148:151], v[2:3], off offset:96
	s_mov_b32 s12, 0xac00
	v_bfe_u32 v173, v167, 6, 2
	v_bfe_u32 v155, v167, 5, 1
	v_mad_i32_i24 v2, v154, s12, 0
	v_lshrrev_b32_e32 v172, 6, v167
	v_add_u32_e32 v3, 0xc800, v2
	v_add_u32_e32 v16, v2, v0
	v_lshlrev_b32_e32 v20, 4, v155
	v_lshl_or_b32 v0, v173, 5, v166
	v_bfe_u32 v5, v172, 1, 1
	v_lshrrev_b32_e32 v17, 1, v6
	v_add_u32_e32 v17, v17, v3
	v_add_u32_e32 v17, 0x6400, v17
	v_mul_u32_u24_e32 v18, 0x190, v8
	v_mul_u32_u24_e32 v19, 0x90, v9
	v_add_u32_e32 v21, v2, v20
	v_mad_u32_u24 v22, v0, s14, 0
	v_lshl_add_u32 v23, v155, 4, v3
	v_mul_u32_u24_e32 v24, 0x190, v166
	v_mul_u32_u24_e32 v25, 0x90, v166
	v_mov_b32_e32 v14, v1
	v_mov_b32_e32 v15, v1
	v_lshl_or_b32 v175, v171, 1, v5
	v_sub_u32_e32 v176, 0x80, v4
	v_mov_b32_e32 v0, v1
	v_mov_b32_e32 v2, v1
	v_mov_b32_e32 v3, v1
	v_mov_b32_e32 v4, v1
	v_mov_b32_e32 v5, v1
	v_mov_b32_e32 v6, v1
	v_mov_b32_e32 v8, v1
	v_mov_b32_e32 v9, v1
	v_mov_b32_e32 v10, v1
	v_mov_b32_e32 v11, v1
	v_mov_b32_e32 v12, v1
	v_mov_b32_e32 v13, v1
	v_add_u32_e32 v178, v16, v18
	v_add_u32_e32 v179, v17, v19
	v_add_u32_e32 v180, v21, v24
	v_add_u32_e32 v181, v22, v20
	v_add_u32_e32 v182, v23, v25
	v_mov_b64_e32 v[30:31], v[14:15]
	v_mov_b64_e32 v[46:47], v[14:15]
	v_mov_b64_e32 v[62:63], v[14:15]
	v_mov_b64_e32 v[78:79], v[14:15]
	v_and_b32_e32 v174, 63, v167
	s_mov_b32 s14, 0
	v_mov_b32_e32 v183, 0xff800000
	v_mov_b32_e32 v177, 0
	s_mov_b64 s[12:13], 0
	v_mov_b32_e32 v246, v154
	v_mov_b64_e32 v[28:29], v[12:13]
	v_mov_b64_e32 v[26:27], v[10:11]
	v_mov_b64_e32 v[24:25], v[8:9]
	v_mov_b64_e32 v[22:23], v[6:7]
	v_mov_b64_e32 v[20:21], v[4:5]
	v_mov_b64_e32 v[18:19], v[2:3]
	v_mov_b64_e32 v[16:17], v[0:1]
	v_mov_b64_e32 v[44:45], v[12:13]
	v_mov_b64_e32 v[42:43], v[10:11]
	v_mov_b64_e32 v[40:41], v[8:9]
	v_mov_b64_e32 v[38:39], v[6:7]
	v_mov_b64_e32 v[36:37], v[4:5]
	v_mov_b64_e32 v[34:35], v[2:3]
	v_mov_b64_e32 v[32:33], v[0:1]
	v_mov_b64_e32 v[60:61], v[12:13]
	v_mov_b64_e32 v[58:59], v[10:11]
	v_mov_b64_e32 v[56:57], v[8:9]
	v_mov_b64_e32 v[54:55], v[6:7]
	v_mov_b64_e32 v[52:53], v[4:5]
	v_mov_b64_e32 v[50:51], v[2:3]
	v_mov_b64_e32 v[48:49], v[0:1]
	v_mov_b64_e32 v[76:77], v[12:13]
	v_mov_b64_e32 v[74:75], v[10:11]
	v_mov_b64_e32 v[72:73], v[8:9]
	v_mov_b64_e32 v[70:71], v[6:7]
	v_mov_b64_e32 v[68:69], v[4:5]
	v_mov_b64_e32 v[66:67], v[2:3]
	v_mov_b64_e32 v[64:65], v[0:1]
	v_readfirstlane_b32 s32, v154
	s_mov_b32 s41, 0
	s_lshl_b32 s40, s32, 16
	v_lshl_add_u64 v[156:157], v[156:157], 0, s[40:41]
	s_lshl_b32 s40, s32, 13
	v_lshl_add_u64 v[158:159], v[158:159], 0, s[40:41]
	s_lshl_b32 s40, s32, 7
	v_lshl_add_u64 v[164:165], v[164:165], 0, s[40:41]
	s_mov_b32 s40, 0x20000
	s_mov_b32 s42, 0x4000
	s_mov_b32 s43, 0
	s_movk_i32 s88, 0x100
	s_mov_b32 s89, 0
	ds_read_b128 v[80:83], v181
	ds_read_b128 v[214:217], v181 offset:32
	ds_read_b128 v[234:237], v181 offset:64
	ds_read_b128 v[238:241], v181 offset:96
	s_cmp_lg_u32 s32, 0
	s_cbranch_scc0 .Lprio_skip
	s_setprio 1

; template <int DK, int DV, int KT, bool SAMPLE>
; DI void attn_item(CP c, int l, int qb, int h, unsigned char* sm) {
;     ...
;     for (int j = 0; j < nj; ++j) {
;         const int kt = 2 * j + g;
;         lds_barrier();
;         if (!SAMPLE) {
; #pragma unroll
;             for (int i = 0; i < 6; ++i) *(u32x4*)(Ks + lkey * QS + ls0 * 8 + i * 32) = kreg[i];
; #pragma unroll
;             for (int i = 0; i < 4; ++i) *(u32x4*)(Vs + ldv * VS + lv0 * 8 + i * 16) = vreg[i];
;         } else {
;             const int k0 = kt * 32;
;             for (int v = gt; v < 32 * 40; v += 256) { const int key = v / 40, s = v % 40, kk = k0 + key; u32x4 o = (u32x4){0u, 0u, 0u, 0u};
;                 if (kk < 2048) { const float* src = s < 32 ? c->in[I_CLAT] + ((size_t)(l * 32 + b) * 2048 + kk) * 256 + s * 8 : c->in[I_CKPE] + ((size_t)(l * 32 + b) * 2048 + kk) * 64 + (s - 32) * 8;
;                     const f32x4 a = *(const f32x4*)src, bq = *(const f32x4*)(src + 4); o.x = pk2(a[0], a[1]); o.y = pk2(a[2], a[3]); o.z = pk2(bq[0], bq[1]); o.w = pk2(bq[2], bq[3]); }
;                 else if (kk < 2064) { const int rr = MP + b * 16 + (kk - 2048); o = *(const u32x4*)(s < 32 ? LATg + (size_t)rr * 256 + s * 8 : KPEg + (size_t)rr * 64 + (s - 32) * 8); }
;                 *(u32x4*)(Ks + key * QS + s * 8) = o; }
;             for (int v = gt; v < 256 * 4; v += 256) { const int dv = v >> 2, s = v & 3; u32x4 o = (u32x4){0u, 0u, 0u, 0u};
;                 if (k0 < LTS) o = *(const u32x4*)(LTg + ((size_t)b * 256 + dv) * LTS + k0 + s * 8);
;                 *(u32x4*)(Vs + dv * VS + s * 8) = o; }
;         }
;         lds_barrier();
;         if (!SAMPLE) { if (j + 1 < nj) ATT_ISSUE(kt + 2); }
;         const bool active = SAMPLE ? (wave_on && kt * 32 < 2064) : (kt <= qc);
;         if (active) {
;             f32x16 S[NMT];
; #pragma unroll
;             for (int mt = 0; mt < NMT; ++mt)
; #pragma unroll
;                 for (int i = 0; i < 16; ++i) S[mt][i] = 0.f;
;             {
;                 constexpr int NKP = DK / 32;
;                 bf16x8 Kf[2][2 * NMT]; bf16x8 Ql[2][2];
; #pragma unroll
;                 for (int e = 0; e < 2; ++e) {
; #pragma unroll
;                     for (int mt = 0; mt < NMT; ++mt) Kf[0][e * NMT + mt] = *(const bf16x8*)(Ks + (32 * mt + l31) * QS + 16 * e + 8 * hh);
.LBB0_647:
	s_waitcnt lgkmcnt(0)
	s_barrier
	s_waitcnt vmcnt(9)
	ds_write_b128 v178, v[112:115] offset:51200
	s_waitcnt vmcnt(8)
	ds_write_b128 v178, v[116:119] offset:51264
	s_waitcnt vmcnt(7)
	ds_write_b128 v178, v[120:123] offset:51328
	s_waitcnt vmcnt(6)
	ds_write_b128 v178, v[124:127] offset:51392
	s_waitcnt vmcnt(5)
	ds_write_b128 v178, v[128:131] offset:51456
	s_waitcnt vmcnt(4)
	ds_write_b128 v178, v[132:135] offset:51520
	s_waitcnt vmcnt(3)
	ds_write2_b64 v179, v[136:137], v[138:139] offset0:0 offset1:2
	s_waitcnt vmcnt(2)
	ds_write2_b64 v179, v[140:141], v[142:143] offset0:4 offset1:6
	s_waitcnt vmcnt(1)
	ds_write2_b64 v179, v[144:145], v[146:147] offset0:8 offset1:10
	s_waitcnt vmcnt(0)
	ds_write2_b64 v179, v[148:149], v[150:151] offset0:12 offset1:14
	s_waitcnt lgkmcnt(0)
	s_barrier
	v_cmp_lt_u32_e32 vcc, s14, v171
	v_add_u32_e32 v2, 2, v246
	s_and_saveexec_b64 s[16:17], vcc
	s_cbranch_execz .LBB0_649
	v_lshl_add_u64 v[156:157], v[156:157], 0, s[40:41]
	v_lshl_add_u64 v[158:159], v[158:159], 0, s[42:43]
	v_lshl_add_u64 v[164:165], v[164:165], 0, s[88:89]
	ds_read_b128 v[4:7], v180 offset:51200
	ds_read_b128 v[8:11], v180 offset:51232
	ds_read_b128 v[12:15], v180 offset:64000
	ds_read_b128 v[184:187], v180 offset:64032
	ds_read_b128 v[218:221], v180 offset:51264
	ds_read_b128 v[222:225], v180 offset:51296
	ds_read_b128 v[226:229], v180 offset:64064
	ds_read_b128 v[230:233], v180 offset:64096
	s_waitcnt lgkmcnt(5)
	v_mfma_f32_32x32x16_bf16 v[96:111], v[4:7], v[80:83], 0
	v_mfma_f32_32x32x16_bf16 v[80:95], v[12:15], v[80:83], 0
	global_load_dwordx4 v[112:115], v[156:157], off
	s_waitcnt lgkmcnt(4)
	v_mfma_f32_32x32x16_bf16 v[96:111], v[8:11], v[214:217], v[96:111]
	v_mfma_f32_32x32x16_bf16 v[80:95], v[184:187], v[214:217], v[80:95]
	ds_read_b128 v[4:7], v180 offset:51328
	ds_read_b128 v[8:11], v180 offset:51360
	ds_read_b128 v[12:15], v180 offset:64128
	ds_read_b128 v[184:187], v180 offset:64160
	ds_read_b128 v[214:217], v181 offset:128
	ds_read_b128 v[242:245], v181 offset:160
	s_waitcnt lgkmcnt(7)
	v_mfma_f32_32x32x16_bf16 v[96:111], v[218:221], v[234:237], v[96:111]
	v_mfma_f32_32x32x16_bf16 v[80:95], v[226:229], v[234:237], v[80:95]
	global_load_dwordx4 v[116:119], v[156:157], off offset:64
	s_waitcnt lgkmcnt(6)
	v_mfma_f32_32x32x16_bf16 v[96:111], v[222:225], v[238:241], v[96:111]
	v_mfma_f32_32x32x16_bf16 v[80:95], v[230:233], v[238:241], v[80:95]
	ds_read_b128 v[218:221], v180 offset:51392
	ds_read_b128 v[222:225], v180 offset:51424
	ds_read_b128 v[226:229], v180 offset:64192
	ds_read_b128 v[230:233], v180 offset:64224
	ds_read_b128 v[234:237], v181 offset:192
	ds_read_b128 v[238:241], v181 offset:224
	s_waitcnt lgkmcnt(7)
	v_mfma_f32_32x32x16_bf16 v[96:111], v[4:7], v[214:217], v[96:111]
	v_mfma_f32_32x32x16_bf16 v[80:95], v[12:15], v[214:217], v[80:95]
	global_load_dwordx4 v[120:123], v[156:157], off offset:128
	s_waitcnt lgkmcnt(6)
	v_mfma_f32_32x32x16_bf16 v[96:111], v[8:11], v[242:245], v[96:111]
	v_mfma_f32_32x32x16_bf16 v[80:95], v[184:187], v[242:245], v[80:95]
	ds_read_b128 v[4:7], v180 offset:51456
	ds_read_b128 v[8:11], v180 offset:51488
	ds_read_b128 v[12:15], v180 offset:64256
	ds_read_b128 v[184:187], v180 offset:64288
	ds_read_b128 v[214:217], v181 offset:256
	ds_read_b128 v[242:245], v181 offset:288
	s_waitcnt lgkmcnt(7)
	v_mfma_f32_32x32x16_bf16 v[96:111], v[218:221], v[234:237], v[96:111]
	v_mfma_f32_32x32x16_bf16 v[80:95], v[226:229], v[234:237], v[80:95]
	global_load_dwordx4 v[124:127], v[156:157], off offset:192
	s_waitcnt lgkmcnt(6)
	v_mfma_f32_32x32x16_bf16 v[96:111], v[222:225], v[238:241], v[96:111]
	v_mfma_f32_32x32x16_bf16 v[80:95], v[230:233], v[238:241], v[80:95]
	ds_read_b128 v[218:221], v180 offset:51520
	ds_read_b128 v[222:225], v180 offset:51552
	ds_read_b128 v[226:229], v180 offset:64320
	ds_read_b128 v[230:233], v180 offset:64352
	ds_read_b128 v[234:237], v181 offset:320
	ds_read_b128 v[238:241], v181 offset:352
	s_waitcnt lgkmcnt(7)
	v_mfma_f32_32x32x16_bf16 v[96:111], v[4:7], v[214:217], v[96:111]
	v_mfma_f32_32x32x16_bf16 v[80:95], v[12:15], v[214:217], v[80:95]
	global_load_dwordx4 v[128:131], v[158:159], off
	s_waitcnt lgkmcnt(6)
	v_mfma_f32_32x32x16_bf16 v[96:111], v[8:11], v[242:245], v[96:111]
	v_mfma_f32_32x32x16_bf16 v[80:95], v[184:187], v[242:245], v[80:95]
	s_waitcnt lgkmcnt(1)
	v_mfma_f32_32x32x16_bf16 v[96:111], v[218:221], v[234:237], v[96:111]
	v_mfma_f32_32x32x16_bf16 v[80:95], v[226:229], v[234:237], v[80:95]
	global_load_dwordx4 v[132:135], v[158:159], off offset:64
	s_waitcnt lgkmcnt(0)
; DI unsigned pk2(float lo, float hi) { const hwf2_t v = {lo, hi}; const hwbf2_t b = __builtin_convertvector(v, hwbf2_t); return __builtin_bit_cast(unsigned, b); }
; #define ATT_LDV(buf, gi) do { const int _kg = (gi) / NDB, _db = (gi) % NDB; _Pragma("unroll") for (int d = 0; d < 4; ++d) { const bf16_t* vp = Vs + (32 * (4 * _db + d) + l31) * VS + 16 * _kg + 4 * hh; \
;                         const u32x2 lo = *(const u32x2*)vp, hi = *(const u32x2*)(vp + 8); Vf[buf][d].x = lo.x; Vf[buf][d].y = lo.y; Vf[buf][d].z = hi.x; Vf[buf][d].w = hi.y; } } while (0)
; template <int DK, int DV, int KT, bool SAMPLE>
; DI void attn_item(CP c, int l, int qb, int h, unsigned char* sm) {
;     ...
;             float mloc = -INFINITY;
; #pragma unroll
;             for (int mt = 0; mt < NMT; ++mt)
; #pragma unroll
;                 for (int i = 0; i < 16; ++i) { float s = S[mt][i] * scale;
;                     if (SAMPLE) { const int key = kt * KT + 32 * mt + (i & 3) + 8 * (i >> 2) + 4 * hh; if (key >= 2064) s = -INFINITY; }
;                     S[mt][i] = s; mloc = fmaxf(mloc, s); }
;             mloc = fmaxf(mloc, __shfl_xor(mloc, 32));
;             const float mnew = fmaxf(m_run, mloc); const float alpha = __builtin_amdgcn_exp2f(m_run - mnew); float psum = 0.f;
; #pragma unroll
;             for (int mt = 0; mt < NMT; ++mt)
; #pragma unroll
;                 for (int i = 0; i < 16; ++i) { const float p = __builtin_amdgcn_exp2f(S[mt][i] - mnew); S[mt][i] = p; psum += p; }
;             l_run = l_run * alpha + psum; m_run = mnew;
; #pragma unroll
;             for (int d = 0; d < NDT; ++d) Oacc[d] = Oacc[d] * alpha;
;             {
;                 constexpr int NDB = NDT / 4;
;                 constexpr int NG = 2 * NMT * NDB;
;                 u32x4 Vf[2][4];
;     ...
;                 ATT_LDV(0, 0);
; #pragma unroll
;                 for (int gi = 0; gi < NG; ++gi) { const int kg = gi / NDB, db = gi % NDB, mt = kg >> 1, s2 = kg & 1;
;                     if (gi + 1 < NG) ATT_LDV((gi + 1) & 1, gi + 1);
;                     u32x4 pw; pw.x = pk2(S[mt][8 * s2 + 0], S[mt][8 * s2 + 1]); pw.y = pk2(S[mt][8 * s2 + 2], S[mt][8 * s2 + 3]);
;                     pw.z = pk2(S[mt][8 * s2 + 4], S[mt][8 * s2 + 5]); pw.w = pk2(S[mt][8 * s2 + 6], S[mt][8 * s2 + 7]);
	v_mfma_f32_32x32x16_bf16 v[96:111], v[222:225], v[238:241], v[96:111]
	v_mfma_f32_32x32x16_bf16 v[80:95], v[230:233], v[238:241], v[80:95]
	s_nop 10
	s_mov_b32 s18, 0xff800000
	v_max3_f32 v0, v96, s18, v97
	v_max3_f32 v0, v0, v98, v99
	v_max3_f32 v0, v0, v100, v101
	v_max3_f32 v0, v0, v102, v103
	v_max3_f32 v0, v0, v104, v105
	v_max3_f32 v0, v0, v106, v107
	v_max3_f32 v0, v0, v108, v109
	v_max3_f32 v0, v0, v110, v111
	v_max3_f32 v0, v0, v80, v81
	v_max3_f32 v0, v0, v82, v83
	v_max3_f32 v0, v0, v84, v85
	v_max3_f32 v0, v0, v86, v87
	v_max3_f32 v0, v0, v88, v89
	v_max3_f32 v0, v0, v90, v91
	v_max3_f32 v0, v0, v92, v93
	v_max3_f32 v0, v0, v94, v95
	s_mov_b32 s18, 0x3dd53b94
	v_mul_f32_e32 v0, 0x3dd53b94, v0
	v_add_u32_e32 v226, 0x6000, v182
	v_mov_b32_e32 v3, v0
	v_mov_b32_e32 v4, v0
	v_add_u32_e32 v227, 0x7000, v182
	v_add_u32_e32 v228, 0x8800, v182
	v_permlane32_swap_b32_e32 v3, v4
	v_add_u32_e32 v229, 0x9800, v182
	v_max3_f32 v3, v183, v3, v4
	v_fma_f32 v4, v96, s18, -v3
	v_sub_f32_e32 v0, v183, v3
	v_exp_f32_e32 v183, v4
	v_fma_f32 v4, v97, s18, -v3
	v_exp_f32_e32 v184, v4
	v_fma_f32 v4, v98, s18, -v3
	v_exp_f32_e32 v185, v4
	v_fma_f32 v4, v99, s18, -v3
	v_exp_f32_e32 v186, v4
	v_fma_f32 v5, v100, s18, -v3
	v_add_f32_e32 v4, 0, v183
	v_exp_f32_e32 v187, v5
	v_fma_f32 v5, v101, s18, -v3
	v_add_f32_e32 v4, v184, v4
	v_exp_f32_e32 v192, v5
	v_fma_f32 v5, v102, s18, -v3
	v_add_f32_e32 v4, v185, v4
	v_exp_f32_e32 v193, v5
	v_fma_f32 v5, v103, s18, -v3
	v_add_f32_e32 v4, v186, v4
	v_exp_f32_e32 v103, v5
	v_fma_f32 v5, v104, s18, -v3
	v_add_f32_e32 v4, v187, v4
	v_exp_f32_e32 v104, v5
	v_fma_f32 v5, v105, s18, -v3
	v_add_f32_e32 v4, v192, v4
	v_exp_f32_e32 v105, v5
	v_fma_f32 v5, v106, s18, -v3
	v_add_f32_e32 v4, v193, v4
	v_exp_f32_e32 v106, v5
	v_fma_f32 v5, v107, s18, -v3
	v_add_f32_e32 v4, v103, v4
	v_exp_f32_e32 v107, v5
	v_fma_f32 v5, v108, s18, -v3
	v_add_f32_e32 v4, v104, v4
	v_exp_f32_e32 v108, v5
	v_fma_f32 v5, v109, s18, -v3
	v_add_f32_e32 v4, v105, v4
	v_exp_f32_e32 v109, v5
	v_fma_f32 v5, v110, s18, -v3
	v_add_f32_e32 v4, v106, v4
	v_exp_f32_e32 v110, v5
	v_fma_f32 v5, v111, s18, -v3
	v_add_f32_e32 v4, v107, v4
	v_exp_f32_e32 v111, v5
	v_fma_f32 v5, v80, s18, -v3
	v_add_f32_e32 v4, v108, v4
	v_exp_f32_e32 v204, v5
	v_fma_f32 v5, v81, s18, -v3
	v_add_f32_e32 v4, v109, v4
	v_exp_f32_e32 v205, v5
	v_fma_f32 v5, v82, s18, -v3
	v_add_f32_e32 v4, v110, v4
	v_exp_f32_e32 v206, v5
	v_fma_f32 v5, v83, s18, -v3
	v_add_f32_e32 v4, v111, v4
	v_exp_f32_e32 v207, v5
	v_fma_f32 v5, v84, s18, -v3
	v_exp_f32_e32 v213, v5
	v_fma_f32 v5, v85, s18, -v3
	v_add_f32_e32 v4, v204, v4
	v_exp_f32_e32 v214, v5
	v_fma_f32 v5, v86, s18, -v3
	v_add_f32_e32 v4, v205, v4
	v_exp_f32_e32 v215, v5
	v_fma_f32 v5, v87, s18, -v3
	v_add_f32_e32 v4, v206, v4
	v_exp_f32_e32 v216, v5
	v_fma_f32 v5, v88, s18, -v3
	v_add_f32_e32 v4, v207, v4
	v_exp_f32_e32 v217, v5
	v_fma_f32 v5, v89, s18, -v3
	v_add_f32_e32 v4, v213, v4
	v_exp_f32_e32 v218, v5
	v_fma_f32 v5, v90, s18, -v3
	v_add_f32_e32 v4, v214, v4
	v_exp_f32_e32 v219, v5
	v_fma_f32 v5, v91, s18, -v3
	v_add_f32_e32 v4, v215, v4
	v_exp_f32_e32 v220, v5
	v_fma_f32 v5, v92, s18, -v3
	v_add_f32_e32 v4, v216, v4
	v_exp_f32_e32 v221, v5
	v_fma_f32 v5, v93, s18, -v3
	v_add_f32_e32 v4, v217, v4
	v_exp_f32_e32 v222, v5
	v_fma_f32 v5, v94, s18, -v3
	v_add_f32_e32 v4, v218, v4
	v_exp_f32_e32 v223, v5
	v_fma_f32 v5, v95, s18, -v3
	v_add_f32_e32 v4, v219, v4
	v_exp_f32_e32 v224, v5
	v_add_f32_e32 v4, v220, v4
	v_add_f32_e32 v4, v221, v4
	v_add_f32_e32 v4, v222, v4
	v_add_f32_e32 v4, v223, v4
	v_add_f32_e32 v225, v224, v4
	ds_read_b128 v[4:7], v226 offset:1024
	ds_read_b128 v[8:11], v226 offset:1056
	ds_read_b128 v[12:15], v227 offset:1536
	ds_read_b128 v[80:83], v228
	ds_read_b128 v[84:87], v229 offset:512
	ds_read_b128 v[88:91], v227 offset:1568
	ds_read_b128 v[92:95], v228 offset:32
	ds_read_b128 v[96:99], v229 offset:544
	v_exp_f32_e32 v0, v0
	v_cvt_pk_bf16_f32 v100, v183, v184
	v_cvt_pk_bf16_f32 v101, v185, v186
	v_cvt_pk_bf16_f32 v102, v187, v192
	v_pk_mul_f32 v[78:79], v[78:79], v[0:1] op_sel_hi:[1,0]
	v_pk_mul_f32 v[76:77], v[76:77], v[0:1] op_sel_hi:[1,0]
	v_pk_mul_f32 v[74:75], v[74:75], v[0:1] op_sel_hi:[1,0]
	v_pk_mul_f32 v[72:73], v[72:73], v[0:1] op_sel_hi:[1,0]
	v_pk_mul_f32 v[70:71], v[70:71], v[0:1] op_sel_hi:[1,0]
	v_pk_mul_f32 v[68:69], v[68:69], v[0:1] op_sel_hi:[1,0]
	v_pk_mul_f32 v[66:67], v[66:67], v[0:1] op_sel_hi:[1,0]
	v_pk_mul_f32 v[64:65], v[64:65], v[0:1] op_sel_hi:[1,0]
	v_pk_mul_f32 v[62:63], v[62:63], v[0:1] op_sel_hi:[1,0]
	v_pk_mul_f32 v[60:61], v[60:61], v[0:1] op_sel_hi:[1,0]
	v_pk_mul_f32 v[58:59], v[58:59], v[0:1] op_sel_hi:[1,0]
	v_pk_mul_f32 v[56:57], v[56:57], v[0:1] op_sel_hi:[1,0]
	v_pk_mul_f32 v[54:55], v[54:55], v[0:1] op_sel_hi:[1,0]
	v_pk_mul_f32 v[52:53], v[52:53], v[0:1] op_sel_hi:[1,0]
	v_pk_mul_f32 v[50:51], v[50:51], v[0:1] op_sel_hi:[1,0]
	v_pk_mul_f32 v[48:49], v[48:49], v[0:1] op_sel_hi:[1,0]
	v_pk_mul_f32 v[46:47], v[46:47], v[0:1] op_sel_hi:[1,0]
	v_pk_mul_f32 v[44:45], v[44:45], v[0:1] op_sel_hi:[1,0]
	v_pk_mul_f32 v[42:43], v[42:43], v[0:1] op_sel_hi:[1,0]
	v_pk_mul_f32 v[40:41], v[40:41], v[0:1] op_sel_hi:[1,0]
	v_pk_mul_f32 v[38:39], v[38:39], v[0:1] op_sel_hi:[1,0]
	v_pk_mul_f32 v[36:37], v[36:37], v[0:1] op_sel_hi:[1,0]
	v_pk_mul_f32 v[34:35], v[34:35], v[0:1] op_sel_hi:[1,0]
	v_pk_mul_f32 v[32:33], v[32:33], v[0:1] op_sel_hi:[1,0]
	v_pk_mul_f32 v[30:31], v[30:31], v[0:1] op_sel_hi:[1,0]
	v_pk_mul_f32 v[28:29], v[28:29], v[0:1] op_sel_hi:[1,0]
	v_pk_mul_f32 v[26:27], v[26:27], v[0:1] op_sel_hi:[1,0]
	v_pk_mul_f32 v[24:25], v[24:25], v[0:1] op_sel_hi:[1,0]
	v_pk_mul_f32 v[22:23], v[22:23], v[0:1] op_sel_hi:[1,0]
	v_pk_mul_f32 v[20:21], v[20:21], v[0:1] op_sel_hi:[1,0]
	v_pk_mul_f32 v[18:19], v[18:19], v[0:1] op_sel_hi:[1,0]
	v_pk_mul_f32 v[16:17], v[16:17], v[0:1] op_sel_hi:[1,0]
	v_cvt_pk_bf16_f32 v103, v193, v103
	s_waitcnt lgkmcnt(7)
; template <int DK, int DV, int KT, bool SAMPLE>
; DI void attn_item(CP c, int l, int qb, int h, unsigned char* sm) {
;     ...
;             {
;                 constexpr int NKP = DK / 32;
;                 bf16x8 Kf[2][2 * NMT]; bf16x8 Ql[2][2];
; #pragma unroll
;                 for (int e = 0; e < 2; ++e) {
; #pragma unroll
;                     for (int mt = 0; mt < NMT; ++mt) Kf[0][e * NMT + mt] = *(const bf16x8*)(Ks + (32 * mt + l31) * QS + 16 * e + 8 * hh);
;                     if (!QREG) Ql[0][e] = *(const bf16x8*)(Qs + (32 * wq + l31) * QS + 16 * e + 8 * hh); }
; #pragma unroll
;                 for (int kp = 0; kp < NKP; ++kp) {
;                     if (kp + 1 < NKP) {
; #pragma unroll
;                         for (int e = 0; e < 2; ++e) {
; #pragma unroll
;                             for (int mt = 0; mt < NMT; ++mt) Kf[(kp + 1) & 1][e * NMT + mt] = *(const bf16x8*)(Ks + (32 * mt + l31) * QS + 16 * (2 * kp + 2 + e) + 8 * hh);
;                             if (!QREG) Ql[(kp + 1) & 1][e] = *(const bf16x8*)(Qs + (32 * wq + l31) * QS + 16 * (2 * kp + 2 + e) + 8 * hh); } }
;                     __builtin_amdgcn_sched_barrier(0);
; #pragma unroll
;                     for (int e = 0; e < 2; ++e)
; #pragma unroll
;                         for (int mt = 0; mt < NMT; ++mt) S[mt] = __builtin_amdgcn_mfma_f32_32x32x16_bf16(Kf[kp & 1][e * NMT + mt], !QREG ? Ql[kp & 1][e] : Qf[QREG ? 2 * kp + e : 0], S[mt], 0, 0, 0);
;                     __builtin_amdgcn_sched_barrier(0);
;     ...
;                 for (int gi = 0; gi < NG; ++gi) { const int kg = gi / NDB, db = gi % NDB, mt = kg >> 1, s2 = kg & 1;
;                     if (gi + 1 < NG) ATT_LDV((gi + 1) & 1, gi + 1);
;                     u32x4 pw; pw.x = pk2(S[mt][8 * s2 + 0], S[mt][8 * s2 + 1]); pw.y = pk2(S[mt][8 * s2 + 2], S[mt][8 * s2 + 3]);
;                     pw.z = pk2(S[mt][8 * s2 + 4], S[mt][8 * s2 + 5]); pw.w = pk2(S[mt][8 * s2 + 6], S[mt][8 * s2 + 7]);
;                     const bf16x8 pf = __builtin_bit_cast(bf16x8, pw);
;                     __builtin_amdgcn_sched_barrier(0);
; #pragma unroll
;                     for (int d = 0; d < 4; ++d) Oacc[4 * db + d] = __builtin_amdgcn_mfma_f32_32x32x16_bf16(__builtin_bit_cast(bf16x8, Vf[gi & 1][d]), pf, Oacc[4 * db + d], 0, 0, 0);
;                     __builtin_amdgcn_sched_barrier(0);
;                 }
	s_nop 0
	v_mfma_f32_32x32x16_bf16 v[64:79], v[4:7], v[100:103], v[64:79]
	s_waitcnt lgkmcnt(5)
	v_mfma_f32_32x32x16_bf16 v[48:63], v[12:15], v[100:103], v[48:63]
	global_load_dwordx4 v[136:139], v[164:165], off
	s_waitcnt lgkmcnt(4)
	v_mfma_f32_32x32x16_bf16 v[32:47], v[80:83], v[100:103], v[32:47]
	s_waitcnt lgkmcnt(3)
	v_mfma_f32_32x32x16_bf16 v[16:31], v[84:87], v[100:103], v[16:31]
	ds_read_b128 v[4:7], v226 offset:1088
	ds_read_b128 v[12:15], v227 offset:1600
	ds_read_b128 v[80:83], v228 offset:64
	ds_read_b128 v[84:87], v229 offset:576
	v_cvt_pk_bf16_f32 v100, v104, v105
	v_cvt_pk_bf16_f32 v101, v106, v107
	v_cvt_pk_bf16_f32 v102, v108, v109
	v_cvt_pk_bf16_f32 v103, v110, v111
	s_nop 1
	v_mfma_f32_32x32x16_bf16 v[64:79], v[8:11], v[100:103], v[64:79]
	s_waitcnt lgkmcnt(6)
	v_mfma_f32_32x32x16_bf16 v[48:63], v[88:91], v[100:103], v[48:63]
	global_load_dwordx4 v[140:143], v[164:165], off offset:32
	s_waitcnt lgkmcnt(5)
	v_mfma_f32_32x32x16_bf16 v[32:47], v[92:95], v[100:103], v[32:47]
	s_waitcnt lgkmcnt(4)
	v_mfma_f32_32x32x16_bf16 v[16:31], v[96:99], v[100:103], v[16:31]
	ds_read_b128 v[8:11], v226 offset:1120
	ds_read_b128 v[88:91], v227 offset:1632
	ds_read_b128 v[92:95], v228 offset:96
	ds_read_b128 v[96:99], v229 offset:608
	v_cvt_pk_bf16_f32 v100, v204, v205
	v_cvt_pk_bf16_f32 v101, v206, v207
	v_cvt_pk_bf16_f32 v102, v213, v214
	v_cvt_pk_bf16_f32 v103, v215, v216
	s_waitcnt lgkmcnt(7)
	s_nop 0
	v_mfma_f32_32x32x16_bf16 v[64:79], v[4:7], v[100:103], v[64:79]
	s_waitcnt lgkmcnt(6)
	v_mfma_f32_32x32x16_bf16 v[48:63], v[12:15], v[100:103], v[48:63]
	global_load_dwordx4 v[144:147], v[164:165], off offset:64
	s_waitcnt lgkmcnt(5)
	v_mfma_f32_32x32x16_bf16 v[32:47], v[80:83], v[100:103], v[32:47]
	s_waitcnt lgkmcnt(4)
	v_mfma_f32_32x32x16_bf16 v[16:31], v[84:87], v[100:103], v[16:31]
	v_cvt_pk_bf16_f32 v4, v217, v218
	v_cvt_pk_bf16_f32 v5, v219, v220
	v_cvt_pk_bf16_f32 v6, v221, v222
	v_cvt_pk_bf16_f32 v7, v223, v224
	s_waitcnt lgkmcnt(3)
	s_nop 0
	v_mfma_f32_32x32x16_bf16 v[64:79], v[8:11], v[4:7], v[64:79]
	s_waitcnt lgkmcnt(2)
	v_mfma_f32_32x32x16_bf16 v[48:63], v[88:91], v[4:7], v[48:63]
	global_load_dwordx4 v[148:151], v[164:165], off offset:96
	s_waitcnt lgkmcnt(1)
	v_mfma_f32_32x32x16_bf16 v[32:47], v[92:95], v[4:7], v[32:47]
	s_waitcnt lgkmcnt(0)
	v_mfma_f32_32x32x16_bf16 v[16:31], v[96:99], v[4:7], v[16:31]
	ds_read_b128 v[80:83], v181
	ds_read_b128 v[214:217], v181 offset:32
	ds_read_b128 v[234:237], v181 offset:64
	ds_read_b128 v[238:241], v181 offset:96
	v_fmac_f32_e32 v225, v177, v0
	v_mov_b32_e32 v177, v225
	v_mov_b32_e32 v183, v3
	s_branch .LBB0_646
.LBB0_649:
	s_or_b64 exec, exec, s[16:17]
	v_cmp_le_i32_e32 vcc, v246, v175
	s_and_saveexec_b64 s[16:17], vcc
	s_cbranch_execz .LBB0_646
	ds_read_b128 v[4:7], v180 offset:51200
	ds_read_b128 v[8:11], v180 offset:51232
	ds_read_b128 v[12:15], v180 offset:64000
	ds_read_b128 v[184:187], v180 offset:64032
	ds_read_b128 v[218:221], v180 offset:51264
	ds_read_b128 v[222:225], v180 offset:51296
	ds_read_b128 v[226:229], v180 offset:64064
	ds_read_b128 v[230:233], v180 offset:64096
	s_waitcnt lgkmcnt(5)
	v_mfma_f32_32x32x16_bf16 v[96:111], v[4:7], v[80:83], 0
	v_mfma_f32_32x32x16_bf16 v[80:95], v[12:15], v[80:83], 0
	s_waitcnt lgkmcnt(4)
	v_mfma_f32_32x32x16_bf16 v[96:111], v[8:11], v[214:217], v[96:111]
	v_mfma_f32_32x32x16_bf16 v[80:95], v[184:187], v[214:217], v[80:95]
	ds_read_b128 v[4:7], v180 offset:51328
	ds_read_b128 v[8:11], v180 offset:51360
	ds_read_b128 v[12:15], v180 offset:64128
	ds_read_b128 v[184:187], v180 offset:64160
	ds_read_b128 v[214:217], v181 offset:128
	ds_read_b128 v[242:245], v181 offset:160
	s_waitcnt lgkmcnt(7)
	v_mfma_f32_32x32x16_bf16 v[96:111], v[218:221], v[234:237], v[96:111]
	v_mfma_f32_32x32x16_bf16 v[80:95], v[226:229], v[234:237], v[80:95]
	s_waitcnt lgkmcnt(6)
	v_mfma_f32_32x32x16_bf16 v[96:111], v[222:225], v[238:241], v[96:111]
	v_mfma_f32_32x32x16_bf16 v[80:95], v[230:233], v[238:241], v[80:95]
	ds_read_b128 v[218:221], v180 offset:51392
	ds_read_b128 v[222:225], v180 offset:51424
	ds_read_b128 v[226:229], v180 offset:64192
	ds_read_b128 v[230:233], v180 offset:64224
	ds_read_b128 v[234:237], v181 offset:192
	ds_read_b128 v[238:241], v181 offset:224
	s_waitcnt lgkmcnt(7)
	v_mfma_f32_32x32x16_bf16 v[96:111], v[4:7], v[214:217], v[96:111]
	v_mfma_f32_32x32x16_bf16 v[80:95], v[12:15], v[214:217], v[80:95]
	s_waitcnt lgkmcnt(6)
	v_mfma_f32_32x32x16_bf16 v[96:111], v[8:11], v[242:245], v[96:111]
	v_mfma_f32_32x32x16_bf16 v[80:95], v[184:187], v[242:245], v[80:95]
	ds_read_b128 v[4:7], v180 offset:51456
	ds_read_b128 v[8:11], v180 offset:51488
	ds_read_b128 v[12:15], v180 offset:64256
	ds_read_b128 v[184:187], v180 offset:64288
	ds_read_b128 v[214:217], v181 offset:256
	ds_read_b128 v[242:245], v181 offset:288
	s_waitcnt lgkmcnt(7)
	v_mfma_f32_32x32x16_bf16 v[96:111], v[218:221], v[234:237], v[96:111]
	v_mfma_f32_32x32x16_bf16 v[80:95], v[226:229], v[234:237], v[80:95]
	s_waitcnt lgkmcnt(6)
	v_mfma_f32_32x32x16_bf16 v[96:111], v[222:225], v[238:241], v[96:111]
	v_mfma_f32_32x32x16_bf16 v[80:95], v[230:233], v[238:241], v[80:95]
	ds_read_b128 v[218:221], v180 offset:51520
	ds_read_b128 v[222:225], v180 offset:51552
	ds_read_b128 v[226:229], v180 offset:64320
	ds_read_b128 v[230:233], v180 offset:64352
	ds_read_b128 v[234:237], v181 offset:320
	ds_read_b128 v[238:241], v181 offset:352
	s_waitcnt lgkmcnt(7)
	v_mfma_f32_32x32x16_bf16 v[96:111], v[4:7], v[214:217], v[96:111]
	v_mfma_f32_32x32x16_bf16 v[80:95], v[12:15], v[214:217], v[80:95]
	s_waitcnt lgkmcnt(6)
	v_mfma_f32_32x32x16_bf16 v[96:111], v[8:11], v[242:245], v[96:111]
	v_mfma_f32_32x32x16_bf16 v[80:95], v[184:187], v[242:245], v[80:95]
	s_waitcnt lgkmcnt(1)
; DI unsigned pk2(float lo, float hi) { const hwf2_t v = {lo, hi}; const hwbf2_t b = __builtin_convertvector(v, hwbf2_t); return __builtin_bit_cast(unsigned, b); }
; #define ATT_LDV(buf, gi) do { const int _kg = (gi) / NDB, _db = (gi) % NDB; _Pragma("unroll") for (int d = 0; d < 4; ++d) { const bf16_t* vp = Vs + (32 * (4 * _db + d) + l31) * VS + 16 * _kg + 4 * hh; \
;                         const u32x2 lo = *(const u32x2*)vp, hi = *(const u32x2*)(vp + 8); Vf[buf][d].x = lo.x; Vf[buf][d].y = lo.y; Vf[buf][d].z = hi.x; Vf[buf][d].w = hi.y; } } while (0)
; template <int DK, int DV, int KT, bool SAMPLE>
; DI void attn_item(CP c, int l, int qb, int h, unsigned char* sm) {
;     ...
;             float mloc = -INFINITY;
; #pragma unroll
;             for (int mt = 0; mt < NMT; ++mt)
; #pragma unroll
;                 for (int i = 0; i < 16; ++i) { float s = S[mt][i] * scale;
;                     if (SAMPLE) { const int key = kt * KT + 32 * mt + (i & 3) + 8 * (i >> 2) + 4 * hh; if (key >= 2064) s = -INFINITY; }
;                     S[mt][i] = s; mloc = fmaxf(mloc, s); }
;             mloc = fmaxf(mloc, __shfl_xor(mloc, 32));
;             const float mnew = fmaxf(m_run, mloc); const float alpha = __builtin_amdgcn_exp2f(m_run - mnew); float psum = 0.f;
; #pragma unroll
;             for (int mt = 0; mt < NMT; ++mt)
; #pragma unroll
;                 for (int i = 0; i < 16; ++i) { const float p = __builtin_amdgcn_exp2f(S[mt][i] - mnew); S[mt][i] = p; psum += p; }
;             l_run = l_run * alpha + psum; m_run = mnew;
; #pragma unroll
;             for (int d = 0; d < NDT; ++d) Oacc[d] = Oacc[d] * alpha;
;             {
;                 constexpr int NDB = NDT / 4;
;                 constexpr int NG = 2 * NMT * NDB;
;                 u32x4 Vf[2][4];
;     ...
;                 ATT_LDV(0, 0);
; #pragma unroll
;                 for (int gi = 0; gi < NG; ++gi) { const int kg = gi / NDB, db = gi % NDB, mt = kg >> 1, s2 = kg & 1;
;                     if (gi + 1 < NG) ATT_LDV((gi + 1) & 1, gi + 1);
;                     u32x4 pw; pw.x = pk2(S[mt][8 * s2 + 0], S[mt][8 * s2 + 1]); pw.y = pk2(S[mt][8 * s2 + 2], S[mt][8 * s2 + 3]);
;                     pw.z = pk2(S[mt][8 * s2 + 4], S[mt][8 * s2 + 5]); pw.w = pk2(S[mt][8 * s2 + 6], S[mt][8 * s2 + 7]);
	v_mfma_f32_32x32x16_bf16 v[96:111], v[218:221], v[234:237], v[96:111]
	v_mfma_f32_32x32x16_bf16 v[80:95], v[226:229], v[234:237], v[80:95]
	s_waitcnt lgkmcnt(0)
	v_mfma_f32_32x32x16_bf16 v[96:111], v[222:225], v[238:241], v[96:111]
	v_mfma_f32_32x32x16_bf16 v[80:95], v[230:233], v[238:241], v[80:95]
	s_nop 10
	s_mov_b32 s18, 0xff800000
	v_max3_f32 v0, v96, s18, v97
	v_max3_f32 v0, v0, v98, v99
	v_max3_f32 v0, v0, v100, v101
	v_max3_f32 v0, v0, v102, v103
	v_max3_f32 v0, v0, v104, v105
	v_max3_f32 v0, v0, v106, v107
	v_max3_f32 v0, v0, v108, v109
	v_max3_f32 v0, v0, v110, v111
	v_max3_f32 v0, v0, v80, v81
	v_max3_f32 v0, v0, v82, v83
	v_max3_f32 v0, v0, v84, v85
	v_max3_f32 v0, v0, v86, v87
	v_max3_f32 v0, v0, v88, v89
	v_max3_f32 v0, v0, v90, v91
	v_max3_f32 v0, v0, v92, v93
	v_max3_f32 v0, v0, v94, v95
	s_mov_b32 s18, 0x3dd53b94
	v_mul_f32_e32 v0, 0x3dd53b94, v0
	v_add_u32_e32 v226, 0x6000, v182
	v_mov_b32_e32 v3, v0
	v_mov_b32_e32 v4, v0
	v_add_u32_e32 v227, 0x7000, v182
	v_add_u32_e32 v228, 0x8800, v182
	v_permlane32_swap_b32_e32 v3, v4
	v_add_u32_e32 v229, 0x9800, v182
	v_max3_f32 v3, v183, v3, v4
	v_fma_f32 v4, v96, s18, -v3
	v_sub_f32_e32 v0, v183, v3
	v_exp_f32_e32 v183, v4
	v_fma_f32 v4, v97, s18, -v3
	v_exp_f32_e32 v184, v4
	v_fma_f32 v4, v98, s18, -v3
	v_exp_f32_e32 v185, v4
	v_fma_f32 v4, v99, s18, -v3
	v_exp_f32_e32 v186, v4
	v_fma_f32 v5, v100, s18, -v3
	v_add_f32_e32 v4, 0, v183
	v_exp_f32_e32 v187, v5
	v_fma_f32 v5, v101, s18, -v3
	v_add_f32_e32 v4, v184, v4
	v_exp_f32_e32 v192, v5
	v_fma_f32 v5, v102, s18, -v3
	v_add_f32_e32 v4, v185, v4
	v_exp_f32_e32 v193, v5
	v_fma_f32 v5, v103, s18, -v3
	v_add_f32_e32 v4, v186, v4
	v_exp_f32_e32 v103, v5
	v_fma_f32 v5, v104, s18, -v3
	v_add_f32_e32 v4, v187, v4
	v_exp_f32_e32 v104, v5
	v_fma_f32 v5, v105, s18, -v3
	v_add_f32_e32 v4, v192, v4
	v_exp_f32_e32 v105, v5
	v_fma_f32 v5, v106, s18, -v3
	v_add_f32_e32 v4, v193, v4
	v_exp_f32_e32 v106, v5
	v_fma_f32 v5, v107, s18, -v3
	v_add_f32_e32 v4, v103, v4
	v_exp_f32_e32 v107, v5
	v_fma_f32 v5, v108, s18, -v3
	v_add_f32_e32 v4, v104, v4
	v_exp_f32_e32 v108, v5
	v_fma_f32 v5, v109, s18, -v3
	v_add_f32_e32 v4, v105, v4
	v_exp_f32_e32 v109, v5
	v_fma_f32 v5, v110, s18, -v3
	v_add_f32_e32 v4, v106, v4
	v_exp_f32_e32 v110, v5
	v_fma_f32 v5, v111, s18, -v3
	v_add_f32_e32 v4, v107, v4
	v_exp_f32_e32 v111, v5
	v_fma_f32 v5, v80, s18, -v3
	v_add_f32_e32 v4, v108, v4
	v_exp_f32_e32 v204, v5
	v_fma_f32 v5, v81, s18, -v3
	v_add_f32_e32 v4, v109, v4
	v_exp_f32_e32 v205, v5
	v_fma_f32 v5, v82, s18, -v3
	v_add_f32_e32 v4, v110, v4
	v_exp_f32_e32 v206, v5
	v_fma_f32 v5, v83, s18, -v3
	v_add_f32_e32 v4, v111, v4
	v_exp_f32_e32 v207, v5
	v_fma_f32 v5, v84, s18, -v3
	v_exp_f32_e32 v213, v5
	v_fma_f32 v5, v85, s18, -v3
	v_add_f32_e32 v4, v204, v4
	v_exp_f32_e32 v214, v5
	v_fma_f32 v5, v86, s18, -v3
	v_add_f32_e32 v4, v205, v4
	v_exp_f32_e32 v215, v5
	v_fma_f32 v5, v87, s18, -v3
	v_add_f32_e32 v4, v206, v4
	v_exp_f32_e32 v216, v5
	v_fma_f32 v5, v88, s18, -v3
	v_add_f32_e32 v4, v207, v4
	v_exp_f32_e32 v217, v5
	v_fma_f32 v5, v89, s18, -v3
	v_add_f32_e32 v4, v213, v4
	v_exp_f32_e32 v218, v5
	v_fma_f32 v5, v90, s18, -v3
	v_add_f32_e32 v4, v214, v4
	v_exp_f32_e32 v219, v5
	v_fma_f32 v5, v91, s18, -v3
	v_add_f32_e32 v4, v215, v4
	v_exp_f32_e32 v220, v5
	v_fma_f32 v5, v92, s18, -v3
	v_add_f32_e32 v4, v216, v4
	v_exp_f32_e32 v221, v5
	v_fma_f32 v5, v93, s18, -v3
	v_add_f32_e32 v4, v217, v4
	v_exp_f32_e32 v222, v5
	v_fma_f32 v5, v94, s18, -v3
	v_add_f32_e32 v4, v218, v4
	v_exp_f32_e32 v223, v5
	v_fma_f32 v5, v95, s18, -v3
	v_add_f32_e32 v4, v219, v4
	v_exp_f32_e32 v224, v5
	v_add_f32_e32 v4, v220, v4
	v_add_f32_e32 v4, v221, v4
	v_add_f32_e32 v4, v222, v4
	v_add_f32_e32 v4, v223, v4
	v_add_f32_e32 v225, v224, v4
	ds_read_b128 v[4:7], v226 offset:1024
	ds_read_b128 v[8:11], v226 offset:1056
	ds_read_b128 v[12:15], v227 offset:1536
	ds_read_b128 v[80:83], v228
	ds_read_b128 v[84:87], v229 offset:512
	ds_read_b128 v[88:91], v227 offset:1568
	ds_read_b128 v[92:95], v228 offset:32
	ds_read_b128 v[96:99], v229 offset:544
	v_exp_f32_e32 v0, v0
	v_cvt_pk_bf16_f32 v100, v183, v184
	v_cvt_pk_bf16_f32 v101, v185, v186
	v_cvt_pk_bf16_f32 v102, v187, v192
	v_pk_mul_f32 v[78:79], v[78:79], v[0:1] op_sel_hi:[1,0]
	v_pk_mul_f32 v[76:77], v[76:77], v[0:1] op_sel_hi:[1,0]
	v_pk_mul_f32 v[74:75], v[74:75], v[0:1] op_sel_hi:[1,0]
	v_pk_mul_f32 v[72:73], v[72:73], v[0:1] op_sel_hi:[1,0]
	v_pk_mul_f32 v[70:71], v[70:71], v[0:1] op_sel_hi:[1,0]
	v_pk_mul_f32 v[68:69], v[68:69], v[0:1] op_sel_hi:[1,0]
	v_pk_mul_f32 v[66:67], v[66:67], v[0:1] op_sel_hi:[1,0]
	v_pk_mul_f32 v[64:65], v[64:65], v[0:1] op_sel_hi:[1,0]
	v_pk_mul_f32 v[62:63], v[62:63], v[0:1] op_sel_hi:[1,0]
	v_pk_mul_f32 v[60:61], v[60:61], v[0:1] op_sel_hi:[1,0]
	v_pk_mul_f32 v[58:59], v[58:59], v[0:1] op_sel_hi:[1,0]
	v_pk_mul_f32 v[56:57], v[56:57], v[0:1] op_sel_hi:[1,0]
	v_pk_mul_f32 v[54:55], v[54:55], v[0:1] op_sel_hi:[1,0]
	v_pk_mul_f32 v[52:53], v[52:53], v[0:1] op_sel_hi:[1,0]
	v_pk_mul_f32 v[50:51], v[50:51], v[0:1] op_sel_hi:[1,0]
	v_pk_mul_f32 v[48:49], v[48:49], v[0:1] op_sel_hi:[1,0]
	v_pk_mul_f32 v[46:47], v[46:47], v[0:1] op_sel_hi:[1,0]
	v_pk_mul_f32 v[44:45], v[44:45], v[0:1] op_sel_hi:[1,0]
	v_pk_mul_f32 v[42:43], v[42:43], v[0:1] op_sel_hi:[1,0]
	v_pk_mul_f32 v[40:41], v[40:41], v[0:1] op_sel_hi:[1,0]
	v_pk_mul_f32 v[38:39], v[38:39], v[0:1] op_sel_hi:[1,0]
	v_pk_mul_f32 v[36:37], v[36:37], v[0:1] op_sel_hi:[1,0]
	v_pk_mul_f32 v[34:35], v[34:35], v[0:1] op_sel_hi:[1,0]
	v_pk_mul_f32 v[32:33], v[32:33], v[0:1] op_sel_hi:[1,0]
	v_pk_mul_f32 v[30:31], v[30:31], v[0:1] op_sel_hi:[1,0]
	v_pk_mul_f32 v[28:29], v[28:29], v[0:1] op_sel_hi:[1,0]
	v_pk_mul_f32 v[26:27], v[26:27], v[0:1] op_sel_hi:[1,0]
	v_pk_mul_f32 v[24:25], v[24:25], v[0:1] op_sel_hi:[1,0]
	v_pk_mul_f32 v[22:23], v[22:23], v[0:1] op_sel_hi:[1,0]
	v_pk_mul_f32 v[20:21], v[20:21], v[0:1] op_sel_hi:[1,0]
	v_pk_mul_f32 v[18:19], v[18:19], v[0:1] op_sel_hi:[1,0]
	v_pk_mul_f32 v[16:17], v[16:17], v[0:1] op_sel_hi:[1,0]
	v_cvt_pk_bf16_f32 v103, v193, v103
	s_waitcnt lgkmcnt(7)
; DI unsigned pk2(float lo, float hi) { const hwf2_t v = {lo, hi}; const hwbf2_t b = __builtin_convertvector(v, hwbf2_t); return __builtin_bit_cast(unsigned, b); }
; #define ATT_LDV(buf, gi) do { const int _kg = (gi) / NDB, _db = (gi) % NDB; _Pragma("unroll") for (int d = 0; d < 4; ++d) { const bf16_t* vp = Vs + (32 * (4 * _db + d) + l31) * VS + 16 * _kg + 4 * hh; \
;                         const u32x2 lo = *(const u32x2*)vp, hi = *(const u32x2*)(vp + 8); Vf[buf][d].x = lo.x; Vf[buf][d].y = lo.y; Vf[buf][d].z = hi.x; Vf[buf][d].w = hi.y; } } while (0)
; template <int DK, int DV, int KT, bool SAMPLE>
; DI void attn_item(CP c, int l, int qb, int h, unsigned char* sm) {
;     ...
;                 for (int gi = 0; gi < NG; ++gi) { const int kg = gi / NDB, db = gi % NDB, mt = kg >> 1, s2 = kg & 1;
;                     if (gi + 1 < NG) ATT_LDV((gi + 1) & 1, gi + 1);
;                     u32x4 pw; pw.x = pk2(S[mt][8 * s2 + 0], S[mt][8 * s2 + 1]); pw.y = pk2(S[mt][8 * s2 + 2], S[mt][8 * s2 + 3]);
;                     pw.z = pk2(S[mt][8 * s2 + 4], S[mt][8 * s2 + 5]); pw.w = pk2(S[mt][8 * s2 + 6], S[mt][8 * s2 + 7]);
;                     const bf16x8 pf = __builtin_bit_cast(bf16x8, pw);
;                     __builtin_amdgcn_sched_barrier(0);
; #pragma unroll
;                     for (int d = 0; d < 4; ++d) Oacc[4 * db + d] = __builtin_amdgcn_mfma_f32_32x32x16_bf16(__builtin_bit_cast(bf16x8, Vf[gi & 1][d]), pf, Oacc[4 * db + d], 0, 0, 0);
;                     __builtin_amdgcn_sched_barrier(0);
;                 }
	s_nop 0
	v_mfma_f32_32x32x16_bf16 v[64:79], v[4:7], v[100:103], v[64:79]
	s_waitcnt lgkmcnt(5)
	v_mfma_f32_32x32x16_bf16 v[48:63], v[12:15], v[100:103], v[48:63]
	s_waitcnt lgkmcnt(4)
	v_mfma_f32_32x32x16_bf16 v[32:47], v[80:83], v[100:103], v[32:47]
	s_waitcnt lgkmcnt(3)
	v_mfma_f32_32x32x16_bf16 v[16:31], v[84:87], v[100:103], v[16:31]
	ds_read_b128 v[4:7], v226 offset:1088
	ds_read_b128 v[12:15], v227 offset:1600
	ds_read_b128 v[80:83], v228 offset:64
	ds_read_b128 v[84:87], v229 offset:576
	v_cvt_pk_bf16_f32 v100, v104, v105
	v_cvt_pk_bf16_f32 v101, v106, v107
	v_cvt_pk_bf16_f32 v102, v108, v109
	v_cvt_pk_bf16_f32 v103, v110, v111
	s_nop 1
	v_mfma_f32_32x32x16_bf16 v[64:79], v[8:11], v[100:103], v[64:79]
	s_waitcnt lgkmcnt(6)
	v_mfma_f32_32x32x16_bf16 v[48:63], v[88:91], v[100:103], v[48:63]
	s_waitcnt lgkmcnt(5)
	v_mfma_f32_32x32x16_bf16 v[32:47], v[92:95], v[100:103], v[32:47]
	s_waitcnt lgkmcnt(4)
	v_mfma_f32_32x32x16_bf16 v[16:31], v[96:99], v[100:103], v[16:31]
	ds_read_b128 v[8:11], v226 offset:1120
	ds_read_b128 v[88:91], v227 offset:1632
	ds_read_b128 v[92:95], v228 offset:96
	ds_read_b128 v[96:99], v229 offset:608
	v_cvt_pk_bf16_f32 v100, v204, v205
	v_cvt_pk_bf16_f32 v101, v206, v207
	v_cvt_pk_bf16_f32 v102, v213, v214
	v_cvt_pk_bf16_f32 v103, v215, v216
	s_waitcnt lgkmcnt(7)
	s_nop 0
	v_mfma_f32_32x32x16_bf16 v[64:79], v[4:7], v[100:103], v[64:79]
	s_waitcnt lgkmcnt(6)
	v_mfma_f32_32x32x16_bf16 v[48:63], v[12:15], v[100:103], v[48:63]
	s_waitcnt lgkmcnt(5)
	v_mfma_f32_32x32x16_bf16 v[32:47], v[80:83], v[100:103], v[32:47]
	s_waitcnt lgkmcnt(4)
	v_mfma_f32_32x32x16_bf16 v[16:31], v[84:87], v[100:103], v[16:31]
	v_cvt_pk_bf16_f32 v4, v217, v218
	v_cvt_pk_bf16_f32 v5, v219, v220
	v_cvt_pk_bf16_f32 v6, v221, v222
	v_cvt_pk_bf16_f32 v7, v223, v224
	s_waitcnt lgkmcnt(3)
	s_nop 0
	v_mfma_f32_32x32x16_bf16 v[64:79], v[8:11], v[4:7], v[64:79]
	s_waitcnt lgkmcnt(2)
	v_mfma_f32_32x32x16_bf16 v[48:63], v[88:91], v[4:7], v[48:63]
	s_waitcnt lgkmcnt(1)
	v_mfma_f32_32x32x16_bf16 v[32:47], v[92:95], v[4:7], v[32:47]
	s_waitcnt lgkmcnt(0)
	v_mfma_f32_32x32x16_bf16 v[16:31], v[96:99], v[4:7], v[16:31]
	ds_read_b128 v[80:83], v181
	ds_read_b128 v[214:217], v181 offset:32
	ds_read_b128 v[234:237], v181 offset:64
	ds_read_b128 v[238:241], v181 offset:96
	v_fmac_f32_e32 v225, v177, v0
	v_mov_b32_e32 v177, v225
	v_mov_b32_e32 v183, v3
	s_branch .LBB0_646
